# adds: LDS bpermute cross-lane exchanges replaced by permlane16/32 swaps in the HGRN prep prefix-sum and the MLA row-max
# baseline (speedup 1.0000x reference)
; #define LAS __attribute__((address_space(3)))
; __device__ __forceinline__ int otid() { int t = threadIdx.x; asm volatile("" : "+v"(t)); return t; }
; template <bool DRY> __device__ __forceinline__ void hgrn_unit(LAS unsigned char* lds, int b, int h, int vs, int layer, bf16_t* Pm, const float* lbraw) {
;     using namespace hg;
;     const int tid = otid(), lane = tid & 63; const int wid = __builtin_amdgcn_readfirstlane(tid >> 6);
;     const size_t tok0 = (size_t)b * SEQ;
;     const int kl = lane & 15, tq = lane >> 4, kch = 16 * wid + kl;
;     (void)layer; (void)lbraw;
;     const bf16_t* qsrc = Pm + (tok0 + 4 * tq) * PW + PC_HQ + h * 128 + (kch & ~1);
;     const bf16_t* fsrc = Pm + (tok0 + 4 * tq) * PW + PC_HF + h * 128 + (kch & ~1);
;     const bool isv = tid < 128; const int vv = tid & 31, vtq = (tid >> 5) & 3;
;     const bf16_t* vsrc = Pm + (tok0 + 4 * vtq) * PW + PC_HI + h * 128 + vs * 32 + (vv & ~1);
;     constexpr int NSTEP = SEQ / 16;
;     for (int i = tid; i < SB / 4; i += NTHREADS) ((LAS unsigned*)(lds + OFF_S + SB))[i] = 0u;
;     Raw ra, rb;
;     load_raw(ra, qsrc, fsrc, vsrc, 0, isv);
;     prep(ra, lds, lane, kch, tq, isv, vv, vtq);
;     load_raw(ra, qsrc, fsrc, vsrc, 1, isv); load_raw(rb, qsrc, fsrc, vsrc, 2, isv);
;     f32x16 sacc = {};
;     const int c16 = lane & 15, kq = lane >> 4, r32 = lane & 31, hh = lane >> 5;
;     __syncthreads();
.LBB0_615:
	s_or_b64 exec, exec, s[6:7]
	s_ashr_i32 s6, s22, 4
	s_ashr_i32 s7, s6, 31
	v_bfe_u32 v9, v3, 4, 2
	s_lshl_b64 s[14:15], s[6:7], 11
	v_lshlrev_b32_e32 v8, 2, v9
	v_or_b32_e32 v0, s14, v8
	v_mov_b64_e32 v[4:5], s[4:5]
	v_bfe_u32 v12, v3, 5, 2
	s_ashr_i32 s28, s10, 6
	s_mov_b32 s65, s28
	v_mad_u64_u32 v[0:1], s[6:7], v0, s24, v[4:5]
	s_lshl_b32 s10, s22, 5
	v_lshl_or_b32 v6, v12, 2, s14
	s_and_b32 s6, s10, 0x180
	v_mad_u64_u32 v[4:5], s[8:9], v6, s24, v[4:5]
	v_and_b32_e32 v7, 15, v3
	s_lshl_b32 s34, s28, 4
	v_mad_i32_i24 v1, s15, v240, v1
	s_lshl_b32 s6, s6, 1
	s_mov_b32 s7, s29
	v_mad_i32_i24 v5, s15, v240, v5
	v_lshl_add_u64 v[0:1], v[0:1], 0, s[6:7]
	v_bitop3_b32 v10, s34, -2, v7 bitop3:0xc8
	v_lshl_add_u64 v[4:5], v[4:5], 0, s[6:7]
	s_and_b32 s7, s10, 0x60
	v_ashrrev_i32_e32 v11, 31, v10
	s_lshl_b32 s8, s7, 1
	s_mul_i32 s41, s14, 0x1d40
	s_add_u32 s38, s4, s41
	s_addc_u32 s39, s5, 0
	s_add_u32 s38, s38, s6
	s_addc_u32 s39, s39, 0
	s_add_u32 s38, s38, 0xd00
	s_addc_u32 s39, s39, 0
	s_mov_b32 s9, s29
	v_and_b32_e32 v6, 30, v3
	v_lshl_add_u64 v[0:1], v[10:11], 1, v[0:1]
	v_lshl_add_u64 v[4:5], v[4:5], 0, s[8:9]
	v_lshlrev_b32_e32 v10, 1, v6
	v_mov_b32_e32 v11, v2
	s_movk_i32 s7, 0x1000
	v_lshl_add_u64 v[4:5], v[4:5], 0, v[10:11]
	v_add_co_u32_e32 v10, vcc, s7, v0
	v_cmp_eq_u32_e64 s[50:51], 3, v9
	s_nop 0
	v_addc_co_u32_e32 v11, vcc, 0, v1, vcc
	v_add_co_u32_e32 v14, vcc, s7, v4
	s_movk_i32 s7, 0x2000
	s_nop 0
	v_addc_co_u32_e32 v15, vcc, 0, v5, vcc
	v_add_co_u32_e32 v16, vcc, s7, v0
	s_movk_i32 s7, 0x3000
	s_nop 0
	v_addc_co_u32_e32 v17, vcc, 0, v1, vcc
	v_add_co_u32_e32 v18, vcc, s7, v4
	s_movk_i32 s7, 0x4000
	s_nop 0
	v_addc_co_u32_e32 v19, vcc, 0, v5, vcc
	v_add_co_u32_e32 v20, vcc, s7, v0
	s_nop 1
	v_addc_co_u32_e32 v21, vcc, 0, v1, vcc
	s_nop 0
	s_nop 0
	s_nop 0
	s_nop 0
	v_add_co_u32_e32 v10, vcc, s7, v4
	s_movk_i32 s7, 0x6000
	s_nop 0
	v_addc_co_u32_e32 v11, vcc, 0, v5, vcc
	v_add_co_u32_e32 v10, vcc, s7, v0
	s_nop 1
	v_addc_co_u32_e32 v11, vcc, 0, v1, vcc
	v_add_co_u32_e32 v18, vcc, s7, v4
	s_movk_i32 s7, 0x440
	s_nop 0
	v_addc_co_u32_e32 v19, vcc, 0, v5, vcc
	s_nop 0
	v_and_b32_e32 v19, 1, v3
	v_cmp_eq_u32_e64 s[44:45], 0, v19
	v_and_b32_e32 v11, 63, v3
	v_cmp_gt_u32_e64 s[46:47], 16, v11
	v_cmp_lt_u32_e64 s[48:49], 31, v11
	v_or_b32_e32 v10, s34, v7
	v_lshl_add_u32 v36, v10, 1, 0
	v_mad_u32_u24 v42, v9, s7, v36
	v_bfe_u32 v140, v234, 4, 2
	v_mul_u32_u24_e32 v136, 0x440, v140
	v_lshrrev_b32_e32 v140, 6, v234
	v_and_b32_e32 v141, 15, v234
	v_lshl_or_b32 v140, v140, 4, v141
	v_lshrrev_b32_e32 v140, 1, v140
	v_lshl_add_u32 v136, v140, 2, v136
	v_add_u32_e32 v136, 0xd400, v136
	v_bfe_i32 v145, v234, 4, 1
	v_and_b32_e32 v144, 1, v234
	v_lshl_add_u32 v144, v144, 1, v136
	v_bfe_u32 v140, v234, 5, 2
	v_and_b32_e32 v141, 31, v234
	v_lshrrev_b32_e32 v141, 1, v141
	v_lshlrev_b32_e32 v141, 2, v141
	v_lshl_add_u32 v137, v140, 8, v141
	v_add_u32_e32 v137, 0xf600, v137
	v_and_b32_e32 v140, 63, v234
	v_lshrrev_b32_e32 v141, 4, v140
	v_lshrrev_b32_e32 v142, 6, v234
	v_and_b32_e32 v143, 3, v142
	v_lshl_add_u32 v141, v143, 2, v141
	v_mul_u32_u24_e32 v138, 0x1d40, v141
	v_and_b32_e32 v141, 15, v140
	v_lshl_add_u32 v138, v141, 4, v138
	v_lshrrev_b32_e32 v142, 2, v142
	v_lshl_add_u32 v138, v142, 10, v138
	v_lshrrev_b32_e32 v141, 2, v140
	v_mul_u32_u24_e32 v139, 0x1d40, v141
	v_and_b32_e32 v141, 3, v140
	v_lshl_add_u32 v139, v141, 4, v139
	v_add_u32_e32 v139, 0x800, v139
	v_add_u32_e32 v139, s8, v139
	s_mul_i32 s64, s65, 0x440
	s_add_i32 s64, s64, 0xd400
	s_mov_b64 s[42:43], s[38:39]
	s_cmp_lg_u32 s65, 7
	s_cbranch_scc1 .Lhg_pro_nov
	s_add_i32 m0, s64, 0
	s_nop 0
	global_load_lds_dwordx4 v138, s[42:43]
	s_mov_b32 m0, 0xf600
	s_nop 0
	global_load_lds_dwordx4 v139, s[42:43]
	s_add_u32 s42, s42, 0x1d400
	s_addc_u32 s43, s43, 0
	s_add_i32 m0, s64, 9792
	s_nop 0
	global_load_lds_dwordx4 v138, s[42:43]
	s_mov_b32 m0, 0x11c40
	s_nop 0
	global_load_lds_dwordx4 v139, s[42:43]
	s_add_u32 s42, s42, 0x1d400
	s_addc_u32 s43, s43, 0
	s_add_i32 m0, s64, 19584
	s_nop 0
	global_load_lds_dwordx4 v138, s[42:43]
	s_mov_b32 m0, 0x14280
	s_nop 0
	global_load_lds_dwordx4 v139, s[42:43]
	s_add_u32 s42, s42, 0x1d400
	s_addc_u32 s43, s43, 0
	s_add_i32 m0, s64, 29376
	s_nop 0
	global_load_lds_dwordx4 v138, s[42:43]
	s_mov_b32 m0, 0x168c0
	s_nop 0
	global_load_lds_dwordx4 v139, s[42:43]
	s_waitcnt vmcnt(4)
	s_branch .Lhg_pro_done

; #define LAS __attribute__((address_space(3)))
; __device__ __forceinline__ unsigned cvtpk(float lo, float hi) { f32x2_t v = {lo, hi}; bf16x2_t b = __builtin_convertvector(v, bf16x2_t); return __builtin_bit_cast(unsigned, b); }
; __device__ __forceinline__ void prep(const Raw& Rin, LAS unsigned char* buf, int lane, int kch, int tq, bool isv, int vv, int vtq) {
;     Raw R = Rin; const bool kodd = kch & 1, vodd = vv & 1;
; #pragma unroll
;     for (int i = 0; i < 4; ++i) { asm volatile("" : "+v"(R.q[i])); asm volatile("" : "+v"(R.f[i])); asm volatile("" : "+v"(R.v[i])); }
;     float qv[4], kk[4], c[4]; float run = 0.f;
; #pragma unroll
;     for (int i = 0; i < 4; ++i) {
;         qv[i] = __uint_as_float(kodd ? (R.q[i] & 0xffff0000u) : (R.q[i] << 16));
;         const float l2 = __uint_as_float(kodd ? (R.f[i] & 0xffff0000u) : (R.f[i] << 16));
;         kk[i] = 1.f - __builtin_amdgcn_exp2f(l2);
;         run += l2; c[i] = run;
;     }
;     const float p1 = __shfl(run, (lane - 16) & 63), p2 = __shfl(run, (lane - 32) & 63), p3 = __shfl(run, (lane - 48) & 63);
;     const float off = (tq >= 1 ? p1 : 0.f) + (tq >= 2 ? p2 : 0.f) + (tq >= 3 ? p3 : 0.f);
;     const float btot = __shfl(off + run, 48 + (lane & 15));
;     unsigned short kf[4];
; #pragma unroll
;     for (int i = 0; i < 4; ++i) {
;         const float bt = off + c[i];
;         const float qf = qv[i] * __builtin_amdgcn_exp2f(bt), kfv = kk[i] * __builtin_amdgcn_exp2f(-bt);
;         const unsigned pk = cvtpk(qf, kfv);
;         *(LAS unsigned short*)(buf + OFF_QF + (4 * tq + i) * STR + kch * 2) = (unsigned short)(pk & 0xffffu);
;         kf[i] = (unsigned short)(pk >> 16);
;         *(LAS unsigned short*)(buf + OFF_KF + (4 * tq + i) * STR + kch * 2) = kf[i];
;     }
;     *(LAS u32x2*)(buf + OFF_KFT + kch * 32 + tq * 8) = (u32x2){(unsigned)kf[0] | ((unsigned)kf[1] << 16), (unsigned)kf[2] | ((unsigned)kf[3] << 16)};
;     if (tq == 0) *(LAS float*)(buf + OFF_D + kch * 4) = __builtin_amdgcn_exp2f(btot);
;     if (isv) { unsigned v0 = vodd ? R.v[0] >> 16 : R.v[0] & 0xffffu, v1 = vodd ? R.v[1] >> 16 : R.v[1] & 0xffffu, v2 = vodd ? R.v[2] >> 16 : R.v[2] & 0xffffu, v3 = vodd ? R.v[3] >> 16 : R.v[3] & 0xffffu;
;         *(LAS u32x2*)(buf + OFF_VT + vv * 32 + vtq * 8) = (u32x2){v0 | (v1 << 16), v2 | (v3 << 16)}; }
; }
.Lhg_nov_a:
	s_add_i32 s41, s7, 1
	s_and_b32 s41, s41, 3
	s_mul_i32 s41, s41, 9792
	v_add_u32_e32 v140, s41, v144
	v_add_u32_e32 v141, s41, v137
	v_mov_b32_e32 v0, 0
	v_mov_b32_e32 v1, 0
	v_mov_b32_e32 v3, 0
	v_mov_b32_e32 v56, 0
	v_mov_b32_e32 v78, 0
	v_mov_b32_e32 v62, 0
	v_mov_b32_e32 v84, 0
	v_mov_b32_e32 v88, 0
	ds_read_u16_d16_hi v0, v140 offset:4352
	ds_read_u16_d16_hi v1, v140 offset:4608
	ds_read_u16_d16_hi v3, v140 offset:4864
	ds_read_u16_d16_hi v56, v140 offset:5120
	ds_read_u16_d16_hi v78, v140
	ds_read_u16_d16_hi v62, v140 offset:256
	ds_read_u16_d16_hi v84, v140 offset:512
	ds_read_u16_d16_hi v88, v140 offset:768
	ds_read_b32 v40, v141
	ds_read_b32 v41, v141 offset:64
	ds_read_b32 v53, v141 offset:128
	ds_read_b32 v64, v141 offset:192
	s_waitcnt lgkmcnt(8)
	v_exp_f32_e32 v81, v0
	v_exp_f32_e32 v83, v1
	v_exp_f32_e32 v87, v3
	v_exp_f32_e32 v54, v56
	v_add_f32_e32 v1, v0, v1
	v_add_f32_e32 v3, v1, v3
	v_add_f32_e32 v63, v3, v56
	v_mov_b32_e32 v146, v63
	v_mov_b32_e32 v147, v63
	v_sub_f32_e32 v81, 1.0, v81
	v_sub_f32_e32 v83, 1.0, v83
	v_permlane16_swap_b32_e32 v146, v147
	v_sub_f32_e32 v87, 1.0, v87
	v_add_f32_e32 v148, v146, v147
	v_mov_b32_e32 v149, v148
	v_and_b32_e32 v150, v146, v145
	s_nop 0
	v_permlane32_swap_b32_e32 v148, v149
	v_cndmask_b32_e64 v52, 0, v148, s[48:49]
	v_add_f32_e32 v52, v52, v150
	s_waitcnt lgkmcnt(0)
	v_add_f32_e32 v0, v0, v52
	v_exp_f32_e32 v80, v0
	v_exp_f32_e64 v79, -v0
	v_add_f32_e32 v1, v1, v52
	v_sub_f32_e32 v91, 1.0, v54
	v_add_f32_e32 v54, v63, v52
	v_exp_f32_e32 v82, v1
	v_exp_f32_e64 v63, -v1
	v_add_f32_e32 v3, v3, v52
	v_pk_mul_f32 v[78:79], v[80:81], v[78:79]
	v_exp_f32_e32 v86, v3
	v_exp_f32_e64 v85, -v3
	v_cvt_pk_bf16_f32 v56, v78, v79
	v_exp_f32_e32 v90, v54
	v_exp_f32_e64 v89, -v54
	v_add_u32_e32 v69, v26, v43
	v_pk_mul_f32 v[62:63], v[82:83], v[62:63]
	v_add_f32_e32 v0, v148, v149
	ds_write_b16_d16_hi v69, v56 offset:18688
	v_cvt_pk_bf16_f32 v1, v62, v63
	v_pk_mul_f32 v[62:63], v[86:87], v[84:85]
	ds_write_b16_d16_hi v69, v1 offset:18960
	v_cvt_pk_bf16_f32 v3, v62, v63
	v_pk_mul_f32 v[78:79], v[90:91], v[88:89]
	ds_write_b16 v69, v1 offset:14608
	v_perm_b32 v62, v1, v56, s17
	v_cvt_pk_bf16_f32 v1, v78, v79
	ds_write_b16_d16_hi v69, v3 offset:19232
	ds_write_b16 v69, v1 offset:15152
	v_lshrrev_b32_e32 v52, 16, v1
	v_perm_b32 v63, v1, v3, s17
	v_add_u32_e32 v1, v27, v37
	ds_write_b16 v69, v56 offset:14336
	ds_write_b16 v69, v3 offset:14880
	ds_write_b16 v69, v52 offset:19504
	ds_write_b64 v1, v[62:63] offset:23040
	s_and_saveexec_b64 s[14:15], s[46:47]
	s_cbranch_execz .LBB0_627
	s_waitcnt lgkmcnt(9)
	v_exp_f32_e32 v0, v0
	v_add_u32_e32 v1, v27, v45
	ds_write_b32 v1, v0 offset:28160

; #define LAS __attribute__((address_space(3)))
; __device__ __forceinline__ unsigned cvtpk(float lo, float hi) { f32x2_t v = {lo, hi}; bf16x2_t b = __builtin_convertvector(v, bf16x2_t); return __builtin_bit_cast(unsigned, b); }
; __device__ __forceinline__ void prep(const Raw& Rin, LAS unsigned char* buf, int lane, int kch, int tq, bool isv, int vv, int vtq) {
;     Raw R = Rin; const bool kodd = kch & 1, vodd = vv & 1;
; #pragma unroll
;     for (int i = 0; i < 4; ++i) { asm volatile("" : "+v"(R.q[i])); asm volatile("" : "+v"(R.f[i])); asm volatile("" : "+v"(R.v[i])); }
;     float qv[4], kk[4], c[4]; float run = 0.f;
; #pragma unroll
;     for (int i = 0; i < 4; ++i) {
;         qv[i] = __uint_as_float(kodd ? (R.q[i] & 0xffff0000u) : (R.q[i] << 16));
;         const float l2 = __uint_as_float(kodd ? (R.f[i] & 0xffff0000u) : (R.f[i] << 16));
;         kk[i] = 1.f - __builtin_amdgcn_exp2f(l2);
;         run += l2; c[i] = run;
;     }
;     const float p1 = __shfl(run, (lane - 16) & 63), p2 = __shfl(run, (lane - 32) & 63), p3 = __shfl(run, (lane - 48) & 63);
;     const float off = (tq >= 1 ? p1 : 0.f) + (tq >= 2 ? p2 : 0.f) + (tq >= 3 ? p3 : 0.f);
;     const float btot = __shfl(off + run, 48 + (lane & 15));
;     unsigned short kf[4];
; #pragma unroll
;     for (int i = 0; i < 4; ++i) {
;         const float bt = off + c[i];
;         const float qf = qv[i] * __builtin_amdgcn_exp2f(bt), kfv = kk[i] * __builtin_amdgcn_exp2f(-bt);
;         const unsigned pk = cvtpk(qf, kfv);
;         *(LAS unsigned short*)(buf + OFF_QF + (4 * tq + i) * STR + kch * 2) = (unsigned short)(pk & 0xffffu);
;         kf[i] = (unsigned short)(pk >> 16);
;         *(LAS unsigned short*)(buf + OFF_KF + (4 * tq + i) * STR + kch * 2) = kf[i];
;     }
;     *(LAS u32x2*)(buf + OFF_KFT + kch * 32 + tq * 8) = (u32x2){(unsigned)kf[0] | ((unsigned)kf[1] << 16), (unsigned)kf[2] | ((unsigned)kf[3] << 16)};
;     if (tq == 0) *(LAS float*)(buf + OFF_D + kch * 4) = __builtin_amdgcn_exp2f(btot);
;     if (isv) { unsigned v0 = vodd ? R.v[0] >> 16 : R.v[0] & 0xffffu, v1 = vodd ? R.v[1] >> 16 : R.v[1] & 0xffffu, v2 = vodd ? R.v[2] >> 16 : R.v[2] & 0xffffu, v3 = vodd ? R.v[3] >> 16 : R.v[3] & 0xffffu;
;         *(LAS u32x2*)(buf + OFF_VT + vv * 32 + vtq * 8) = (u32x2){v0 | (v1 << 16), v2 | (v3 << 16)}; }
; }
.Lhg_nov_b:
	s_add_i32 s41, s7, 2
	s_and_b32 s41, s41, 3
	s_mul_i32 s41, s41, 9792
	v_add_u32_e32 v140, s41, v144
	v_add_u32_e32 v141, s41, v137
	v_mov_b32_e32 v0, 0
	v_mov_b32_e32 v1, 0
	v_mov_b32_e32 v3, 0
	v_mov_b32_e32 v72, 0
	v_mov_b32_e32 v66, 0
	v_mov_b32_e32 v82, 0
	v_mov_b32_e32 v74, 0
	v_mov_b32_e32 v76, 0
	ds_read_u16_d16_hi v0, v140 offset:4352
	ds_read_u16_d16_hi v1, v140 offset:4608
	ds_read_u16_d16_hi v3, v140 offset:4864
	ds_read_u16_d16_hi v72, v140 offset:5120
	ds_read_u16_d16_hi v66, v140
	ds_read_u16_d16_hi v82, v140 offset:256
	ds_read_u16_d16_hi v74, v140 offset:512
	ds_read_u16_d16_hi v76, v140 offset:768
	ds_read_b32 v42, v141
	ds_read_b32 v55, v141 offset:64
	ds_read_b32 v65, v141 offset:128
	ds_read_b32 v70, v141 offset:192
	s_waitcnt lgkmcnt(8)
	v_exp_f32_e32 v81, v0
	v_exp_f32_e32 v85, v1
	v_exp_f32_e32 v87, v3
	v_exp_f32_e32 v68, v72
	v_add_f32_e32 v1, v0, v1
	v_add_f32_e32 v3, v1, v3
	v_add_f32_e32 v75, v3, v72
	v_mov_b32_e32 v146, v75
	v_mov_b32_e32 v147, v75
	v_sub_f32_e32 v81, 1.0, v81
	v_sub_f32_e32 v85, 1.0, v85
	v_permlane16_swap_b32_e32 v146, v147
	v_sub_f32_e32 v87, 1.0, v87
	v_add_f32_e32 v148, v146, v147
	v_mov_b32_e32 v149, v148
	v_and_b32_e32 v150, v146, v145
	s_nop 0
	v_permlane32_swap_b32_e32 v148, v149
	v_cndmask_b32_e64 v72, 0, v148, s[48:49]
	v_add_f32_e32 v72, v72, v150
	s_waitcnt lgkmcnt(0)
	v_add_f32_e32 v0, v0, v72
	v_exp_f32_e32 v80, v0
	v_exp_f32_e64 v67, -v0
	v_add_f32_e32 v1, v1, v72
	v_exp_f32_e32 v84, v1
	v_exp_f32_e64 v83, -v1
	v_sub_f32_e32 v89, 1.0, v68
	v_add_f32_e32 v68, v75, v72
	v_add_f32_e32 v3, v3, v72
	v_pk_mul_f32 v[66:67], v[80:81], v[66:67]
	v_exp_f32_e32 v86, v3
	v_exp_f32_e64 v75, -v3
	v_exp_f32_e32 v88, v68
	v_exp_f32_e64 v77, -v68
	v_cvt_pk_bf16_f32 v79, v66, v67
	v_add_f32_e32 v0, v148, v149
	v_add_u32_e32 v80, v36, v43
	v_pk_mul_f32 v[66:67], v[84:85], v[82:83]
	ds_write_b16_d16_hi v80, v79 offset:4352
	v_cvt_pk_bf16_f32 v1, v66, v67
	v_pk_mul_f32 v[66:67], v[86:87], v[74:75]
	v_pk_mul_f32 v[74:75], v[88:89], v[76:77]
	ds_write_b16 v80, v1 offset:272
	ds_write_b16_d16_hi v80, v1 offset:4624
	v_cvt_pk_bf16_f32 v3, v66, v67
	v_perm_b32 v66, v1, v79, s17
	v_cvt_pk_bf16_f32 v1, v74, v75
	v_lshrrev_b32_e32 v68, 16, v1
	ds_write_b16 v80, v79
	ds_write_b16 v80, v3 offset:544
	ds_write_b16_d16_hi v80, v3 offset:4896
	ds_write_b16 v80, v1 offset:816
	v_perm_b32 v67, v1, v3, s17
	ds_write_b16 v80, v68 offset:5168
	ds_write_b64 v38, v[66:67] offset:8704
	s_and_saveexec_b64 s[14:15], s[46:47]
	s_cbranch_execz .LBB0_638
	s_waitcnt lgkmcnt(9)
	v_exp_f32_e32 v0, v0
	v_add_u32_e32 v1, v27, v45
	ds_write_b32 v1, v0 offset:13824

; #define LAS __attribute__((address_space(3)))
; template <bool DRY> __device__ __forceinline__ void mla_unit(LAS unsigned char* lds, int b, int h, int qb, const bf16_t* Q, const bf16_t* Kn, const bf16_t* Pm, const bf16_t* VT, bf16_t* Y) {
;     ...
;         if (t <= tmax) {
;             f32x16 p0 = {}, p1 = {};
; #pragma unroll
;             for (int s = 0; s < 6; ++s) {
;                 const bf16x8 a0 = *(const LAS bf16x8*)(kbuf + r32 * MLA_KSTR + s * 32 + hi * 16);
;                 const bf16x8 a1 = *(const LAS bf16x8*)(kbuf + (32 + r32) * MLA_KSTR + s * 32 + hi * 16);
;                 p0 = __builtin_amdgcn_mfma_f32_32x32x16_bf16(a0, qf[s], p0, 0, 0, 0);
;                 p1 = __builtin_amdgcn_mfma_f32_32x32x16_bf16(a1, qf[s], p1, 0, 0, 0);
;             }
;             float mx = fmaxf(p0[0], p1[0]);
; #pragma unroll
;             for (int r = 1; r < 16; ++r) mx = fmaxf(mx, fmaxf(p0[r], p1[r]));
;             mx = fmaxf(mx, __shfl_xor(mx, 32));
;             const float cand = mx * C; const bool grow = cand > m_run + 8.f;
;             const float m_new = grow ? cand : m_run; const bool anyg = __any(grow);
;             const float alpha = anyg ? __builtin_amdgcn_exp2f(m_run - m_new) : 1.f; m_run = m_new;
;             float ls = 0.f;
; #pragma unroll
;             for (int r = 0; r < 16; ++r) { p0[r] = __builtin_amdgcn_exp2f(p0[r] * C - m_new); p1[r] = __builtin_amdgcn_exp2f(p1[r] * C - m_new); ls += p0[r] + p1[r]; }
;             if (anyg) { l_run *= alpha;
; #pragma unroll
;                 for (int r = 0; r < 16; ++r) { o0[r] *= alpha; o1[r] *= alpha; } }
;             l_run += ls;
.LBB0_806:
	s_cmp_gt_i32 s57, s56
	s_cbranch_scc1 .LBB0_810
	v_add3_u32 v0, s58, v113, v108
	ds_read_b128 v[36:39], v0
	ds_read_b128 v[132:135], v0 offset:32
	ds_read_b128 v[52:55], v0 offset:6656
	ds_read_b128 v[136:139], v0 offset:6688
	ds_read_b128 v[140:143], v0 offset:64
	ds_read_b128 v[144:147], v0 offset:6720
	ds_read_b128 v[148:151], v0 offset:96
	ds_read_b128 v[152:155], v0 offset:6752
	ds_read_b128 v[156:159], v0 offset:128
	ds_read_b128 v[160:163], v0 offset:6784
	ds_read_b128 v[164:167], v0 offset:6816
	ds_read_b128 v[168:171], v0 offset:160
	s_waitcnt lgkmcnt(11)
	v_mfma_f32_32x32x16_bf16 v[36:51], v[36:39], v[84:87], 0
	s_waitcnt lgkmcnt(10)
	v_mfma_f32_32x32x16_bf16 v[36:51], v[132:135], v[68:71], v[36:51]
	s_waitcnt lgkmcnt(9)
	v_mfma_f32_32x32x16_bf16 v[52:67], v[52:55], v[84:87], 0
	s_waitcnt lgkmcnt(8)
	v_mfma_f32_32x32x16_bf16 v[52:67], v[136:139], v[68:71], v[52:67]
	s_waitcnt lgkmcnt(7)
	v_mfma_f32_32x32x16_bf16 v[36:51], v[140:143], v[72:75], v[36:51]
	s_waitcnt lgkmcnt(6)
	v_mfma_f32_32x32x16_bf16 v[52:67], v[144:147], v[72:75], v[52:67]
	s_waitcnt lgkmcnt(5)
	v_mfma_f32_32x32x16_bf16 v[36:51], v[148:151], v[76:79], v[36:51]
	s_waitcnt lgkmcnt(4)
	v_mfma_f32_32x32x16_bf16 v[52:67], v[152:155], v[76:79], v[52:67]
	s_waitcnt lgkmcnt(3)
	v_mfma_f32_32x32x16_bf16 v[36:51], v[156:159], v[80:83], v[36:51]
	s_waitcnt lgkmcnt(2)
	v_mfma_f32_32x32x16_bf16 v[52:67], v[160:163], v[80:83], v[52:67]
	s_waitcnt lgkmcnt(1)
	v_mfma_f32_32x32x16_bf16 v[52:67], v[164:167], v[92:95], v[52:67]
	s_waitcnt lgkmcnt(0)
	v_mfma_f32_32x32x16_bf16 v[36:51], v[168:171], v[92:95], v[36:51]
	v_add3_u32 v130, s23, v120, v106
	v_add_u32_e32 v129, 0x7800, v130
	v_add_u32_e32 v130, 0x6800, v130
	ds_read2_b64 v[172:175], v130 offset1:2
	ds_read2_b64 v[176:179], v129 offset0:64 offset1:66
	ds_read2_b64 v[180:183], v130 offset0:4 offset1:6
	ds_read2_b64 v[184:187], v129 offset0:68 offset1:70
	ds_read2_b64 v[188:191], v130 offset0:8 offset1:10
	ds_read2_b64 v[192:195], v129 offset0:72 offset1:74
	ds_read2_b64 v[196:199], v130 offset0:12 offset1:14
	ds_read2_b64 v[212:215], v129 offset0:76 offset1:78
	s_nop 1
	v_max3_f32 v0, v36, v52, v37
	v_max3_f32 v1, v53, v38, v54
	v_max3_f32 v0, v0, v39, v55
	v_max3_f32 v1, v1, v40, v56
	v_max3_f32 v0, v0, v41, v57
	v_max3_f32 v1, v1, v42, v58
	v_max3_f32 v0, v0, v43, v59
	v_max3_f32 v1, v1, v44, v60
	v_max3_f32 v0, v0, v45, v61
	v_max3_f32 v1, v1, v46, v62
	v_max3_f32 v0, v0, v47, v63
	v_max3_f32 v1, v1, v48, v64
	v_max3_f32 v0, v0, v49, v65
	v_max3_f32 v1, v1, v50, v66
	v_max3_f32 v0, v0, v51, v67
	v_max_f32_e32 v0, v0, v1
	v_mov_b32_e32 v1, v0
	v_mov_b32_e32 v3, v0
	s_nop 1
	v_permlane32_swap_b32_e32 v1, v3
	v_max_f32_e32 v0, v1, v3
	v_mul_f32_e32 v0, 0x3e16c740, v0
	v_add_f32_e32 v1, 0x41000000, v122
	v_cmp_gt_f32_e32 vcc, v0, v1
	s_nop 1
	v_cndmask_b32_e32 v0, v122, v0, vcc
	s_cbranch_vccz .LBB0_809
	v_sub_f32_e32 v1, v122, v0
	v_exp_f32_e32 v122, v1
	s_nop 0
	v_pk_mul_f32 v[34:35], v[34:35], v[122:123] op_sel_hi:[1,0]
	v_pk_mul_f32 v[32:33], v[32:33], v[122:123] op_sel_hi:[1,0]
	v_pk_mul_f32 v[30:31], v[30:31], v[122:123] op_sel_hi:[1,0]
	v_pk_mul_f32 v[28:29], v[28:29], v[122:123] op_sel_hi:[1,0]
	v_pk_mul_f32 v[26:27], v[26:27], v[122:123] op_sel_hi:[1,0]
	v_pk_mul_f32 v[24:25], v[24:25], v[122:123] op_sel_hi:[1,0]
	v_pk_mul_f32 v[22:23], v[22:23], v[122:123] op_sel_hi:[1,0]
	v_pk_mul_f32 v[20:21], v[20:21], v[122:123] op_sel_hi:[1,0]
	v_pk_mul_f32 v[18:19], v[18:19], v[122:123] op_sel_hi:[1,0]
	v_pk_mul_f32 v[16:17], v[16:17], v[122:123] op_sel_hi:[1,0]
	v_pk_mul_f32 v[14:15], v[14:15], v[122:123] op_sel_hi:[1,0]
	v_pk_mul_f32 v[12:13], v[12:13], v[122:123] op_sel_hi:[1,0]
	v_pk_mul_f32 v[10:11], v[10:11], v[122:123] op_sel_hi:[1,0]
	v_pk_mul_f32 v[8:9], v[8:9], v[122:123] op_sel_hi:[1,0]
	v_pk_mul_f32 v[6:7], v[6:7], v[122:123] op_sel_hi:[1,0]
	v_pk_mul_f32 v[4:5], v[4:5], v[122:123] op_sel_hi:[1,0]
	v_mul_f32_e32 v121, v121, v122
